# grid barrier: L1 invalidate issued before the poll/writeback instead of after the release is observed (overlaps its latency with the wait)
# speedup vs baseline: 1.0074x; 1.0027x over previous
; __device__ __forceinline__ unsigned xb_ld(unsigned* p)              { return __hip_atomic_load(p, __ATOMIC_RELAXED, __HIP_MEMORY_SCOPE_AGENT); }
; __device__ __forceinline__ unsigned xb_add(unsigned* p, unsigned v) { return __hip_atomic_fetch_add(p, v, __ATOMIC_RELAXED, __HIP_MEMORY_SCOPE_AGENT); }
; #define XB_SPIN(cond, bar) do { unsigned _sp = 0; while (cond) { __builtin_amdgcn_s_sleep(1); \
;     if ((++_sp & 255u) == 0u) { if (xb_ld(&(bar)[XB_TMO])) break; if (_sp > XB_SPIN_CAP) { atomicAdd(&(bar)[XB_TMO], 1u); break; } } } } while (0)
; __device__ __forceinline__ void xcd_barrier(const XcdBarrier& b) {
;     ...
;         const unsigned old = xb_add(&bar[XB_XSUB(b.x)], 1u);
;         const unsigned gen = old / nloc;
;         if (old + 1u == (gen + 1u) * nloc) {
;             __builtin_amdgcn_fence(__ATOMIC_RELEASE, "agent");
;             asm volatile("s_waitcnt vmcnt(0)" ::: "memory");
;             const unsigned og = xb_add(&bar[XB_TOP], 1u);
;             const unsigned tg = og / nx;
;             if (og + 1u == (tg + 1u) * nx) xb_add(&bar[XB_TOPGEN], 1u);
;             else XB_SPIN(xb_ld(&bar[XB_TOPGEN]) == tg, bar);
;             __builtin_amdgcn_fence(__ATOMIC_ACQUIRE, "agent");
;             xb_add(&bar[XB_XGEN(b.x)], 1u);
;             asm volatile("s_waitcnt vmcnt(0)" ::: "memory");
;         } else {
;             XB_SPIN(xb_ld(&bar[XB_XGEN(b.x)]) == gen, bar);
.LBB0_153:
	s_or_b64 exec, exec, s[10:11]
	v_cvt_f32_u32_e32 v4, v2
	s_waitcnt vmcnt(0)
	v_readfirstlane_b32 s6, v3
	v_sub_u32_e32 v3, 0, v2
	v_rcp_iflag_f32_e32 v4, v4
	v_add_u32_e32 v5, s6, v1
	v_mul_f32_e32 v4, 0x4f7ffffe, v4
	v_cvt_u32_f32_e32 v4, v4
	v_mul_lo_u32 v1, v3, v4
	v_mul_hi_u32 v1, v4, v1
	v_add_u32_e32 v1, v4, v1
	v_mul_hi_u32 v1, v5, v1
	v_mul_lo_u32 v3, v1, v2
	v_sub_u32_e32 v3, v5, v3
	v_add_u32_e32 v4, 1, v1
	v_cmp_ge_u32_e32 vcc, v3, v2
	s_nop 1
	v_cndmask_b32_e32 v1, v1, v4, vcc
	v_sub_u32_e32 v4, v3, v2
	v_cndmask_b32_e32 v3, v3, v4, vcc
	v_add_u32_e32 v4, 1, v1
	v_cmp_ge_u32_e32 vcc, v3, v2
	v_add_u32_e32 v3, 1, v5
	s_nop 0
	v_cndmask_b32_e32 v1, v1, v4, vcc
	v_mul_lo_u32 v4, v2, v1
	v_add_u32_e32 v2, v4, v2
	v_cmp_ne_u32_e32 vcc, v3, v2
	s_and_saveexec_b64 s[6:7], vcc
	s_xor_b64 s[10:11], exec, s[6:7]
	s_cbranch_execz .LBB0_167
	v_readlane_b32 s4, v254, 3
	v_readlane_b32 s5, v254, 4
	s_waitcnt lgkmcnt(0)
	s_nop 3
	buffer_inv sc1
	global_load_dword v0, v195, s[4:5] sc1
	s_waitcnt vmcnt(0)
	v_cmp_eq_u32_e32 vcc, v0, v1
	s_and_saveexec_b64 s[20:21], vcc
	s_cbranch_execz .LBB0_166
	s_mov_b32 s6, 1
	s_mov_b64 s[24:25], 0
	s_branch .LBB0_157

; __device__ __forceinline__ unsigned xb_ld(unsigned* p)              { return __hip_atomic_load(p, __ATOMIC_RELAXED, __HIP_MEMORY_SCOPE_AGENT); }
; __device__ __forceinline__ unsigned xb_add(unsigned* p, unsigned v) { return __hip_atomic_fetch_add(p, v, __ATOMIC_RELAXED, __HIP_MEMORY_SCOPE_AGENT); }
; #define XB_SPIN(cond, bar) do { unsigned _sp = 0; while (cond) { __builtin_amdgcn_s_sleep(1); \
;     if ((++_sp & 255u) == 0u) { if (xb_ld(&(bar)[XB_TMO])) break; if (_sp > XB_SPIN_CAP) { atomicAdd(&(bar)[XB_TMO], 1u); break; } } } } while (0)
; __device__ __forceinline__ void xcd_barrier(const XcdBarrier& b) {
;     ...
;         const unsigned old = xb_add(&bar[XB_XSUB(b.x)], 1u);
;         const unsigned gen = old / nloc;
;         if (old + 1u == (gen + 1u) * nloc) {
;             __builtin_amdgcn_fence(__ATOMIC_RELEASE, "agent");
;             asm volatile("s_waitcnt vmcnt(0)" ::: "memory");
;             const unsigned og = xb_add(&bar[XB_TOP], 1u);
;             const unsigned tg = og / nx;
;             if (og + 1u == (tg + 1u) * nx) xb_add(&bar[XB_TOPGEN], 1u);
;             else XB_SPIN(xb_ld(&bar[XB_TOPGEN]) == tg, bar);
;             __builtin_amdgcn_fence(__ATOMIC_ACQUIRE, "agent");
;             xb_add(&bar[XB_XGEN(b.x)], 1u);
;     ...
;             XB_SPIN(xb_ld(&bar[XB_XGEN(b.x)]) == gen, bar);
;             __builtin_amdgcn_fence(__ATOMIC_ACQUIRE, "agent");
;             asm volatile("s_waitcnt vmcnt(0)" ::: "memory");
.LBB0_166:
	s_or_b64 exec, exec, s[20:21]
	s_waitcnt vmcnt(0)
	s_waitcnt vmcnt(0)
.LBB0_167:
	s_andn2_saveexec_b64 s[6:7], s[10:11]
	s_cbranch_execz .LBB0_187
	s_mov_b64 s[10:11], exec
	buffer_inv sc1
	buffer_wbl2 sc1
	s_waitcnt lgkmcnt(0)
	s_waitcnt vmcnt(0)
	v_mbcnt_lo_u32_b32 v1, s10, 0
	v_mbcnt_hi_u32_b32 v1, s11, v1
	v_cmp_eq_u32_e32 vcc, 0, v1
	s_and_saveexec_b64 s[20:21], vcc
	s_cbranch_execz .LBB0_170
	s_bcnt1_i32_b64 s6, s[10:11]
	v_readlane_b32 s4, v254, 5
	v_mov_b32_e32 v2, s6
	v_readlane_b32 s5, v254, 6
	s_nop 4
	global_atomic_add v2, v195, v2, s[4:5] sc0

; __device__ __forceinline__ unsigned xb_ld(unsigned* p)              { return __hip_atomic_load(p, __ATOMIC_RELAXED, __HIP_MEMORY_SCOPE_AGENT); }
; __device__ __forceinline__ unsigned xb_add(unsigned* p, unsigned v) { return __hip_atomic_fetch_add(p, v, __ATOMIC_RELAXED, __HIP_MEMORY_SCOPE_AGENT); }
; #define XB_SPIN(cond, bar) do { unsigned _sp = 0; while (cond) { __builtin_amdgcn_s_sleep(1); \
;     if ((++_sp & 255u) == 0u) { if (xb_ld(&(bar)[XB_TMO])) break; if (_sp > XB_SPIN_CAP) { atomicAdd(&(bar)[XB_TMO], 1u); break; } } } } while (0)
; __device__ __forceinline__ void xcd_barrier(const XcdBarrier& b) {
;     ...
;             if (og + 1u == (tg + 1u) * nx) xb_add(&bar[XB_TOPGEN], 1u);
;             else XB_SPIN(xb_ld(&bar[XB_TOPGEN]) == tg, bar);
;             __builtin_amdgcn_fence(__ATOMIC_ACQUIRE, "agent");
;             xb_add(&bar[XB_XGEN(b.x)], 1u);
.LBB0_184:
	s_or_b64 exec, exec, s[10:11]
	s_mov_b64 s[10:11], exec
	v_mbcnt_lo_u32_b32 v0, s10, 0
	v_mbcnt_hi_u32_b32 v0, s11, v0
	v_cmp_eq_u32_e32 vcc, 0, v0
	s_waitcnt vmcnt(0)
	s_and_saveexec_b64 s[20:21], vcc
	s_cbranch_execz .LBB0_186
	s_bcnt1_i32_b64 s6, s[10:11]
	v_readlane_b32 s4, v254, 3
	v_mov_b32_e32 v0, s6
	v_readlane_b32 s5, v254, 4
	s_nop 4
	global_atomic_add v195, v0, s[4:5]

; __device__ __forceinline__ unsigned xb_ld(unsigned* p)              { return __hip_atomic_load(p, __ATOMIC_RELAXED, __HIP_MEMORY_SCOPE_AGENT); }
; __device__ __forceinline__ unsigned xb_add(unsigned* p, unsigned v) { return __hip_atomic_fetch_add(p, v, __ATOMIC_RELAXED, __HIP_MEMORY_SCOPE_AGENT); }
; #define XB_SPIN(cond, bar) do { unsigned _sp = 0; while (cond) { __builtin_amdgcn_s_sleep(1); \
;     if ((++_sp & 255u) == 0u) { if (xb_ld(&(bar)[XB_TMO])) break; if (_sp > XB_SPIN_CAP) { atomicAdd(&(bar)[XB_TMO], 1u); break; } } } } while (0)
; __device__ __forceinline__ void xcd_barrier(const XcdBarrier& b) {
;     ...
;         const unsigned old = xb_add(&bar[XB_XSUB(b.x)], 1u);
;         const unsigned gen = old / nloc;
;         if (old + 1u == (gen + 1u) * nloc) {
;             __builtin_amdgcn_fence(__ATOMIC_RELEASE, "agent");
;             asm volatile("s_waitcnt vmcnt(0)" ::: "memory");
;             const unsigned og = xb_add(&bar[XB_TOP], 1u);
;             const unsigned tg = og / nx;
;             if (og + 1u == (tg + 1u) * nx) xb_add(&bar[XB_TOPGEN], 1u);
;             else XB_SPIN(xb_ld(&bar[XB_TOPGEN]) == tg, bar);
;             __builtin_amdgcn_fence(__ATOMIC_ACQUIRE, "agent");
;             xb_add(&bar[XB_XGEN(b.x)], 1u);
;             asm volatile("s_waitcnt vmcnt(0)" ::: "memory");
;         } else {
;             XB_SPIN(xb_ld(&bar[XB_XGEN(b.x)]) == gen, bar);
.LBB0_318:
	s_or_b64 exec, exec, s[20:21]
	v_cvt_f32_u32_e32 v4, v2
	s_waitcnt vmcnt(0)
	v_readfirstlane_b32 s4, v3
	v_sub_u32_e32 v3, 0, v2
	v_rcp_iflag_f32_e32 v4, v4
	v_add_u32_e32 v5, s4, v1
	v_mul_f32_e32 v4, 0x4f7ffffe, v4
	v_cvt_u32_f32_e32 v4, v4
	v_mul_lo_u32 v1, v3, v4
	v_mul_hi_u32 v1, v4, v1
	v_add_u32_e32 v1, v4, v1
	v_mul_hi_u32 v1, v5, v1
	v_mul_lo_u32 v3, v1, v2
	v_sub_u32_e32 v3, v5, v3
	v_add_u32_e32 v4, 1, v1
	v_cmp_ge_u32_e32 vcc, v3, v2
	s_nop 1
	v_cndmask_b32_e32 v1, v1, v4, vcc
	v_sub_u32_e32 v4, v3, v2
	v_cndmask_b32_e32 v3, v3, v4, vcc
	v_add_u32_e32 v4, 1, v1
	v_cmp_ge_u32_e32 vcc, v3, v2
	v_add_u32_e32 v3, 1, v5
	s_nop 0
	v_cndmask_b32_e32 v1, v1, v4, vcc
	v_mul_lo_u32 v4, v2, v1
	v_add_u32_e32 v2, v4, v2
	v_cmp_ne_u32_e32 vcc, v3, v2
	s_and_saveexec_b64 s[6:7], vcc
	s_xor_b64 s[20:21], exec, s[6:7]
	s_cbranch_execz .LBB0_332
	v_readlane_b32 s4, v254, 3
	v_readlane_b32 s5, v254, 4
	s_waitcnt lgkmcnt(0)
	s_nop 3
	buffer_inv sc1
	global_load_dword v0, v195, s[4:5] sc1
	s_waitcnt vmcnt(0)
	v_cmp_eq_u32_e32 vcc, v0, v1
	s_and_saveexec_b64 s[24:25], vcc
	s_cbranch_execz .LBB0_331
	s_mov_b32 s6, 1
	s_mov_b64 s[36:37], 0
	s_branch .LBB0_322

; __device__ __forceinline__ unsigned xb_ld(unsigned* p)              { return __hip_atomic_load(p, __ATOMIC_RELAXED, __HIP_MEMORY_SCOPE_AGENT); }
; __device__ __forceinline__ unsigned xb_add(unsigned* p, unsigned v) { return __hip_atomic_fetch_add(p, v, __ATOMIC_RELAXED, __HIP_MEMORY_SCOPE_AGENT); }
; #define XB_SPIN(cond, bar) do { unsigned _sp = 0; while (cond) { __builtin_amdgcn_s_sleep(1); \
;     if ((++_sp & 255u) == 0u) { if (xb_ld(&(bar)[XB_TMO])) break; if (_sp > XB_SPIN_CAP) { atomicAdd(&(bar)[XB_TMO], 1u); break; } } } } while (0)
; __device__ __forceinline__ void xcd_barrier(const XcdBarrier& b) {
;     ...
;         if (old + 1u == (gen + 1u) * nloc) {
;             __builtin_amdgcn_fence(__ATOMIC_RELEASE, "agent");
;             asm volatile("s_waitcnt vmcnt(0)" ::: "memory");
;             const unsigned og = xb_add(&bar[XB_TOP], 1u);
;             const unsigned tg = og / nx;
;             if (og + 1u == (tg + 1u) * nx) xb_add(&bar[XB_TOPGEN], 1u);
;             else XB_SPIN(xb_ld(&bar[XB_TOPGEN]) == tg, bar);
;             __builtin_amdgcn_fence(__ATOMIC_ACQUIRE, "agent");
;             xb_add(&bar[XB_XGEN(b.x)], 1u);
;     ...
;             XB_SPIN(xb_ld(&bar[XB_XGEN(b.x)]) == gen, bar);
;             __builtin_amdgcn_fence(__ATOMIC_ACQUIRE, "agent");
;             asm volatile("s_waitcnt vmcnt(0)" ::: "memory");
.LBB0_331:
	s_or_b64 exec, exec, s[24:25]
	s_waitcnt vmcnt(0)
	s_waitcnt vmcnt(0)
.LBB0_332:
	s_andn2_saveexec_b64 s[6:7], s[20:21]
	s_cbranch_execz .LBB0_352
	s_mov_b64 s[20:21], exec
	buffer_inv sc1
	buffer_wbl2 sc1
	s_waitcnt lgkmcnt(0)
	s_waitcnt vmcnt(0)
	v_mbcnt_lo_u32_b32 v1, s20, 0
	v_mbcnt_hi_u32_b32 v1, s21, v1
	v_cmp_eq_u32_e32 vcc, 0, v1
	s_and_saveexec_b64 s[24:25], vcc
	s_cbranch_execz .LBB0_335
	s_bcnt1_i32_b64 s4, s[20:21]
	v_mov_b32_e32 v2, s4
	v_readlane_b32 s4, v254, 5
	v_readlane_b32 s5, v254, 6
	s_nop 4
	global_atomic_add v2, v195, v2, s[4:5] sc0

; __device__ __forceinline__ unsigned xb_ld(unsigned* p)              { return __hip_atomic_load(p, __ATOMIC_RELAXED, __HIP_MEMORY_SCOPE_AGENT); }
; __device__ __forceinline__ unsigned xb_add(unsigned* p, unsigned v) { return __hip_atomic_fetch_add(p, v, __ATOMIC_RELAXED, __HIP_MEMORY_SCOPE_AGENT); }
; #define XB_SPIN(cond, bar) do { unsigned _sp = 0; while (cond) { __builtin_amdgcn_s_sleep(1); \
;     if ((++_sp & 255u) == 0u) { if (xb_ld(&(bar)[XB_TMO])) break; if (_sp > XB_SPIN_CAP) { atomicAdd(&(bar)[XB_TMO], 1u); break; } } } } while (0)
; __device__ __forceinline__ void xcd_barrier(const XcdBarrier& b) {
;     ...
;             if (og + 1u == (tg + 1u) * nx) xb_add(&bar[XB_TOPGEN], 1u);
;             else XB_SPIN(xb_ld(&bar[XB_TOPGEN]) == tg, bar);
;             __builtin_amdgcn_fence(__ATOMIC_ACQUIRE, "agent");
;             xb_add(&bar[XB_XGEN(b.x)], 1u);
.LBB0_349:
	s_or_b64 exec, exec, s[20:21]
	s_mov_b64 s[20:21], exec
	v_mbcnt_lo_u32_b32 v0, s20, 0
	v_mbcnt_hi_u32_b32 v0, s21, v0
	v_cmp_eq_u32_e32 vcc, 0, v0
	s_waitcnt vmcnt(0)
	s_and_saveexec_b64 s[24:25], vcc
	s_cbranch_execz .LBB0_351
	s_bcnt1_i32_b64 s4, s[20:21]
	v_mov_b32_e32 v0, s4
	v_readlane_b32 s4, v254, 3
	v_readlane_b32 s5, v254, 4
	s_nop 4
	global_atomic_add v195, v0, s[4:5]

; __device__ __forceinline__ unsigned xb_ld(unsigned* p)              { return __hip_atomic_load(p, __ATOMIC_RELAXED, __HIP_MEMORY_SCOPE_AGENT); }
; __device__ __forceinline__ unsigned xb_add(unsigned* p, unsigned v) { return __hip_atomic_fetch_add(p, v, __ATOMIC_RELAXED, __HIP_MEMORY_SCOPE_AGENT); }
; #define XB_SPIN(cond, bar) do { unsigned _sp = 0; while (cond) { __builtin_amdgcn_s_sleep(1); \
;     if ((++_sp & 255u) == 0u) { if (xb_ld(&(bar)[XB_TMO])) break; if (_sp > XB_SPIN_CAP) { atomicAdd(&(bar)[XB_TMO], 1u); break; } } } } while (0)
; __device__ __forceinline__ void xcd_barrier(const XcdBarrier& b) {
;     ...
;         const unsigned old = xb_add(&bar[XB_XSUB(b.x)], 1u);
;         const unsigned gen = old / nloc;
;         if (old + 1u == (gen + 1u) * nloc) {
;             __builtin_amdgcn_fence(__ATOMIC_RELEASE, "agent");
;             asm volatile("s_waitcnt vmcnt(0)" ::: "memory");
;             const unsigned og = xb_add(&bar[XB_TOP], 1u);
;             const unsigned tg = og / nx;
;             if (og + 1u == (tg + 1u) * nx) xb_add(&bar[XB_TOPGEN], 1u);
;             else XB_SPIN(xb_ld(&bar[XB_TOPGEN]) == tg, bar);
;             __builtin_amdgcn_fence(__ATOMIC_ACQUIRE, "agent");
;             xb_add(&bar[XB_XGEN(b.x)], 1u);
;             asm volatile("s_waitcnt vmcnt(0)" ::: "memory");
;         } else {
;             XB_SPIN(xb_ld(&bar[XB_XGEN(b.x)]) == gen, bar);
.LBB0_401:
	s_or_b64 exec, exec, s[10:11]
	v_cvt_f32_u32_e32 v4, v2
	s_waitcnt vmcnt(0)
	v_readfirstlane_b32 s4, v3
	v_sub_u32_e32 v3, 0, v2
	v_rcp_iflag_f32_e32 v4, v4
	v_add_u32_e32 v5, s4, v1
	v_mul_f32_e32 v4, 0x4f7ffffe, v4
	v_cvt_u32_f32_e32 v4, v4
	v_mul_lo_u32 v1, v3, v4
	v_mul_hi_u32 v1, v4, v1
	v_add_u32_e32 v1, v4, v1
	v_mul_hi_u32 v1, v5, v1
	v_mul_lo_u32 v3, v1, v2
	v_sub_u32_e32 v3, v5, v3
	v_add_u32_e32 v4, 1, v1
	v_cmp_ge_u32_e32 vcc, v3, v2
	s_nop 1
	v_cndmask_b32_e32 v1, v1, v4, vcc
	v_sub_u32_e32 v4, v3, v2
	v_cndmask_b32_e32 v3, v3, v4, vcc
	v_add_u32_e32 v4, 1, v1
	v_cmp_ge_u32_e32 vcc, v3, v2
	v_add_u32_e32 v3, 1, v5
	s_nop 0
	v_cndmask_b32_e32 v1, v1, v4, vcc
	v_mul_lo_u32 v4, v2, v1
	v_add_u32_e32 v2, v4, v2
	v_cmp_ne_u32_e32 vcc, v3, v2
	s_and_saveexec_b64 s[6:7], vcc
	s_xor_b64 s[10:11], exec, s[6:7]
	s_cbranch_execz .LBB0_415
	v_readlane_b32 s4, v254, 3
	v_readlane_b32 s5, v254, 4
	s_waitcnt lgkmcnt(0)
	s_nop 3
	buffer_inv sc1
	global_load_dword v0, v195, s[4:5] sc1
	s_waitcnt vmcnt(0)
	v_cmp_eq_u32_e32 vcc, v0, v1
	s_and_saveexec_b64 s[20:21], vcc
	s_cbranch_execz .LBB0_414
	s_mov_b32 s6, 1
	s_mov_b64 s[24:25], 0
	s_branch .LBB0_405

; __device__ __forceinline__ unsigned xb_add(unsigned* p, unsigned v) { return __hip_atomic_fetch_add(p, v, __ATOMIC_RELAXED, __HIP_MEMORY_SCOPE_AGENT); }
; __device__ __forceinline__ void xcd_barrier(const XcdBarrier& b) {
;     ...
;         if (old + 1u == (gen + 1u) * nloc) {
;             __builtin_amdgcn_fence(__ATOMIC_RELEASE, "agent");
;             asm volatile("s_waitcnt vmcnt(0)" ::: "memory");
;             const unsigned og = xb_add(&bar[XB_TOP], 1u);
;             const unsigned tg = og / nx;
.LBB0_415:
	s_andn2_saveexec_b64 s[6:7], s[10:11]
	s_cbranch_execz .LBB0_435
	s_mov_b64 s[10:11], exec
	buffer_inv sc1
	buffer_wbl2 sc1
	s_waitcnt lgkmcnt(0)
	s_waitcnt vmcnt(0)
	v_mbcnt_lo_u32_b32 v1, s10, 0
	v_mbcnt_hi_u32_b32 v1, s11, v1
	v_cmp_eq_u32_e32 vcc, 0, v1
	s_and_saveexec_b64 s[20:21], vcc
	s_cbranch_execz .LBB0_418
	s_bcnt1_i32_b64 s4, s[10:11]
	v_mov_b32_e32 v2, s4
	v_readlane_b32 s4, v254, 5
	v_readlane_b32 s5, v254, 6
	s_nop 4
	global_atomic_add v2, v195, v2, s[4:5] sc0

; __device__ __forceinline__ unsigned xb_ld(unsigned* p)              { return __hip_atomic_load(p, __ATOMIC_RELAXED, __HIP_MEMORY_SCOPE_AGENT); }
; __device__ __forceinline__ unsigned xb_add(unsigned* p, unsigned v) { return __hip_atomic_fetch_add(p, v, __ATOMIC_RELAXED, __HIP_MEMORY_SCOPE_AGENT); }
; #define XB_SPIN(cond, bar) do { unsigned _sp = 0; while (cond) { __builtin_amdgcn_s_sleep(1); \
;     if ((++_sp & 255u) == 0u) { if (xb_ld(&(bar)[XB_TMO])) break; if (_sp > XB_SPIN_CAP) { atomicAdd(&(bar)[XB_TMO], 1u); break; } } } } while (0)
; __device__ __forceinline__ void xcd_barrier(const XcdBarrier& b) {
;     ...
;             if (og + 1u == (tg + 1u) * nx) xb_add(&bar[XB_TOPGEN], 1u);
;             else XB_SPIN(xb_ld(&bar[XB_TOPGEN]) == tg, bar);
;             __builtin_amdgcn_fence(__ATOMIC_ACQUIRE, "agent");
;             xb_add(&bar[XB_XGEN(b.x)], 1u);
.LBB0_432:
	s_or_b64 exec, exec, s[10:11]
	s_mov_b64 s[10:11], exec
	v_mbcnt_lo_u32_b32 v0, s10, 0
	v_mbcnt_hi_u32_b32 v0, s11, v0
	v_cmp_eq_u32_e32 vcc, 0, v0
	s_waitcnt vmcnt(0)
	s_and_saveexec_b64 s[20:21], vcc
	s_cbranch_execz .LBB0_434
	s_bcnt1_i32_b64 s4, s[10:11]
	v_mov_b32_e32 v0, s4
	v_readlane_b32 s4, v254, 3
	v_readlane_b32 s5, v254, 4
	s_nop 4
	global_atomic_add v195, v0, s[4:5]

; __device__ __forceinline__ unsigned xb_ld(unsigned* p)              { return __hip_atomic_load(p, __ATOMIC_RELAXED, __HIP_MEMORY_SCOPE_AGENT); }
; __device__ __forceinline__ unsigned xb_add(unsigned* p, unsigned v) { return __hip_atomic_fetch_add(p, v, __ATOMIC_RELAXED, __HIP_MEMORY_SCOPE_AGENT); }
; #define XB_SPIN(cond, bar) do { unsigned _sp = 0; while (cond) { __builtin_amdgcn_s_sleep(1); \
;     if ((++_sp & 255u) == 0u) { if (xb_ld(&(bar)[XB_TMO])) break; if (_sp > XB_SPIN_CAP) { atomicAdd(&(bar)[XB_TMO], 1u); break; } } } } while (0)
; __device__ __forceinline__ void xcd_barrier(const XcdBarrier& b) {
;     ...
;             if (og + 1u == (tg + 1u) * nx) xb_add(&bar[XB_TOPGEN], 1u);
;             else XB_SPIN(xb_ld(&bar[XB_TOPGEN]) == tg, bar);
;             __builtin_amdgcn_fence(__ATOMIC_ACQUIRE, "agent");
;             xb_add(&bar[XB_XGEN(b.x)], 1u);
.LBB0_817:
	s_or_b64 exec, exec, s[10:11]
	s_mov_b64 s[10:11], exec
	v_mbcnt_lo_u32_b32 v0, s10, 0
	v_mbcnt_hi_u32_b32 v0, s11, v0
	v_cmp_eq_u32_e32 vcc, 0, v0
	s_waitcnt vmcnt(0)
	s_and_saveexec_b64 s[20:21], vcc
	s_cbranch_execz .LBB0_104
	s_bcnt1_i32_b64 s4, s[10:11]
	v_mov_b32_e32 v0, s4
	v_readlane_b32 s4, v254, 3
	v_readlane_b32 s5, v254, 4
	s_nop 4
	global_atomic_add v195, v0, s[4:5]
	s_branch .LBB0_104
